# lambda table loop (one workgroup per layer): second element's load issued up front so the second iteration hits L2
# baseline (speedup 1.0000x reference)
; #define TIDX tid_opaque()
; __device__ void convert_phase(unsigned char* smem, const Params& p, int l) {
;     ...
;     float* sm = (float*)(((unsigned char*)ldp(38)) + OFF_SM);
;     if (blockIdx.x == 0) { for (int i = TIDX; i < 1024; i += 512) sm[i] = 0.0f; }
;     if (blockIdx.x == 2 % gridDim.x) { const float* lam = ((const float*)ldp(25)) + l * 1024; for (int i = TIDX; i < 1024; i += 512) sm[4224 + i] = -8.0f * log1pf(expf(-lam[i])); }
.LBB0_367:
	v_cvt_f32_u32_e32 v0, s5
	s_sub_i32 s6, 0, s5
	v_rcp_iflag_f32_e32 v0, v0
	s_nop 0
	v_mul_f32_e32 v0, 0x4f7ffffe, v0
	v_cvt_u32_f32_e32 v0, v0
	s_nop 0
	v_readfirstlane_b32 s7, v0
	s_mul_i32 s6, s6, s7
	s_mul_hi_u32 s6, s7, s6
	s_add_i32 s7, s7, s6
	s_lshr_b32 s6, s7, 31
	s_mul_i32 s6, s6, s5
	s_sub_i32 s6, 2, s6
	s_sub_i32 s7, s6, s5
	s_cmp_ge_u32 s6, s5
	s_cselect_b32 s6, s7, s6
	s_sub_i32 s7, s6, s5
	s_cmp_ge_u32 s6, s5
	s_cselect_b32 s6, s7, s6
	s_cmp_lg_u32 s2, s6
	s_cbranch_scc1 .LBB0_372
	s_add_i32 s6, 0, 0x23ec8
	s_cmp_lg_u32 s6, -1
	s_cselect_b32 s6, s6, 0
	s_cselect_b32 s7, s41, 0
	v_mov_b32_e32 v0, s6
	v_mov_b32_e32 v1, s7
	ds_read_b64 v[2:3], v0
	s_waitcnt vmcnt(0) lgkmcnt(0)
	v_mov_b32_e32 v0, v234
	s_movk_i32 s6, 0x400
	s_waitcnt lgkmcnt(0)
	v_readfirstlane_b32 s8, v3
	v_readfirstlane_b32 s9, v2
	v_cmp_gt_i32_e32 vcc, s6, v0
	s_and_saveexec_b64 s[6:7], vcc
	s_movk_i32 s16, 0x1ff
	s_mov_b64 s[14:15], 0x800
	s_cbranch_execz .LBB0_371
	v_readlane_b32 s10, v255, 52
	v_readlane_b32 s11, v255, 53
	s_lshl_b64 s[10:11], s[10:11], 12
	v_ashrrev_i32_e32 v1, 31, v0
	v_lshlrev_b64 v[2:3], 2, v[0:1]
	s_add_u32 s10, s9, s10
	v_add_u32_e32 v4, 0xfffffe00, v0
	v_lshl_add_u64 v[0:1], s[0:1], 0, v[2:3]
	s_mov_b64 s[12:13], 0x22c04200
	s_addc_u32 s11, s8, s11
	v_lshl_add_u64 v[0:1], v[0:1], 0, s[12:13]
	v_lshl_add_u64 v[2:3], s[10:11], 0, v[2:3]
	s_mov_b64 s[8:9], 0
	global_load_dword v48, v[2:3], off offset:2048
